# v26 + next-layer w_uq/w_ukv/gate-weight conversion moved from phase D to A-start (WGs 128-255), colsum_up only on WGs 128-255
# speedup vs baseline: 1.0003x; 1.0003x over previous
.LBB0_259:
	s_cmp_eq_u32 s52, 0
	v_readlane_b32 s12, v254, 50
	s_cselect_b64 s[0:1], -1, 0
	v_readlane_b32 s13, v254, 51
	v_readlane_b32 s26, v255, 0
	v_readlane_b32 s27, v255, 1
	v_writelane_b32 v255, s0, 13
	s_mov_b64 s[64:65], s[28:29]
	s_mov_b32 s53, s13
	s_mul_hi_u32 s34, s52, 0x16800
	s_mul_i32 s35, s52, 0x16800
	v_writelane_b32 v255, s1, 14
	s_and_b64 vcc, exec, s[0:1]
	v_readlane_b32 s14, v254, 52
	v_readlane_b32 s15, v254, 53
	v_readlane_b32 s16, v254, 54
	v_readlane_b32 s17, v254, 55
	v_readlane_b32 s18, v254, 56
	v_readlane_b32 s19, v254, 57
	v_readlane_b32 s20, v254, 58
	v_readlane_b32 s21, v254, 59
	v_readlane_b32 s22, v254, 60
	v_readlane_b32 s23, v254, 61
	v_readlane_b32 s24, v254, 62
	v_readlane_b32 s25, v254, 63
	s_cbranch_vccnz .Lmy_cvt0
	v_readlane_b32 s0, v252, 0
	v_mbcnt_lo_u32_b32 v1, -1, 0
	v_mbcnt_hi_u32_b32 v1, -1, v1
	s_nop 1
	v_or_b32_e32 v0, s0, v1
	v_ashrrev_i32_e32 v0, 6, v0
	v_readlane_b32 s0, v252, 38
	s_nop 1
	v_add_u32_e32 v0, s0, v0
	s_movk_i32 s100, 0xfc00
	s_cmp_lt_u32 s2, 0x80
	s_cselect_b32 s100, 0x2000, s100
	v_add_u32_e32 v0, s100, v0
	v_cmp_gt_i32_e32 vcc, s63, v0
	s_and_saveexec_b64 s[4:5], vcc
	s_cbranch_execz .LBB0_265
	s_add_u32 s8, s28, s35
	v_readlane_b32 s12, v252, 61
	s_addc_u32 s9, s29, s34
	s_lshl_b64 s[0:1], s[52:53], 13
	v_readlane_b32 s14, v252, 63
	v_readlane_b32 s15, v253, 0
	s_add_u32 s6, s14, s0
	v_and_b32_e32 v1, 63, v1
	s_addc_u32 s7, s15, s1
	v_lshlrev_b32_e32 v46, 5, v1
	global_load_dwordx4 v[2:5], v46, s[6:7]
	global_load_dwordx4 v[6:9], v46, s[6:7] offset:16
	global_load_dwordx4 v[10:13], v46, s[6:7] offset:2048
	global_load_dwordx4 v[14:17], v46, s[6:7] offset:2064
	v_or_b32_e32 v54, 0x1000, v46
	v_or_b32_e32 v62, 0x1800, v46
	global_load_dwordx4 v[18:21], v54, s[6:7]
	global_load_dwordx4 v[22:25], v54, s[6:7] offset:16
	global_load_dwordx4 v[26:29], v62, s[6:7]
	global_load_dwordx4 v[30:33], v62, s[6:7] offset:16
	v_readlane_b32 s16, v253, 1
	v_readlane_b32 s17, v253, 2
	s_add_u32 s0, s16, s0
	s_addc_u32 s1, s17, s1
	global_load_dwordx4 v[34:37], v46, s[0:1]
	global_load_dwordx4 v[38:41], v46, s[0:1] offset:16
	global_load_dwordx4 v[42:45], v46, s[0:1] offset:2048
	s_nop 0
	global_load_dwordx4 v[46:49], v46, s[0:1] offset:2064
	s_nop 0
	global_load_dwordx4 v[50:53], v54, s[0:1]
	s_nop 0
	global_load_dwordx4 v[54:57], v54, s[0:1] offset:16
	s_nop 0
	global_load_dwordx4 v[58:61], v62, s[0:1]
	s_nop 0
	global_load_dwordx4 v[62:65], v62, s[0:1] offset:16
	s_add_u32 s6, s8, 0xe216800
	s_addc_u32 s7, s9, 0
	v_readlane_b32 s0, v252, 43
	s_add_u32 s8, s8, 0xe21e800
	v_lshlrev_b32_e32 v160, 4, v1
	v_readlane_b32 s1, v252, 44
	s_addc_u32 s9, s9, 0
	v_cmp_eq_u32_e32 vcc, 0, v1
	s_mov_b64 s[40:41], 0
	v_readlane_b32 s13, v252, 62
	v_readlane_b32 s18, v253, 3
	v_readlane_b32 s19, v253, 4
	v_readlane_b32 s20, v253, 5
	v_readlane_b32 s21, v253, 6
	v_readlane_b32 s22, v253, 7
	v_readlane_b32 s23, v253, 8
	v_readlane_b32 s24, v253, 9
	v_readlane_b32 s25, v253, 10
	v_readlane_b32 s26, v253, 11
	v_readlane_b32 s27, v253, 12
	s_waitcnt vmcnt(15)
	v_rcp_f32_e32 v2, v2
	v_rcp_f32_e32 v3, v3
	s_waitcnt vmcnt(14)
	v_rcp_f32_e32 v71, v9
	v_rcp_f32_e32 v66, v4
	v_rcp_f32_e32 v67, v5
	v_rcp_f32_e32 v68, v6
	v_rcp_f32_e32 v69, v7
	v_rcp_f32_e32 v70, v8
	s_waitcnt vmcnt(13)
	v_rcp_f32_e32 v72, v10
	v_rcp_f32_e32 v73, v11
	v_rcp_f32_e32 v74, v12
	v_rcp_f32_e32 v75, v13
	s_waitcnt vmcnt(12)
	v_rcp_f32_e32 v76, v14
	v_rcp_f32_e32 v77, v15
	v_rcp_f32_e32 v78, v16
	v_rcp_f32_e32 v79, v17
	s_waitcnt vmcnt(11)
	v_rcp_f32_e32 v80, v18
	v_rcp_f32_e32 v81, v19
	v_rcp_f32_e32 v82, v20
	v_rcp_f32_e32 v83, v21
	s_waitcnt vmcnt(10)
	v_rcp_f32_e32 v84, v22
	v_rcp_f32_e32 v85, v23
	v_rcp_f32_e32 v86, v24
	v_rcp_f32_e32 v87, v25
	s_waitcnt vmcnt(9)
	v_rcp_f32_e32 v88, v26
	v_rcp_f32_e32 v89, v27
	v_rcp_f32_e32 v90, v28
	v_rcp_f32_e32 v91, v29
	s_waitcnt vmcnt(8)
	v_rcp_f32_e32 v92, v30
	v_rcp_f32_e32 v93, v31
	s_waitcnt vmcnt(7)
	v_mul_f32_e32 v4, v34, v2
	v_mul_f32_e32 v5, v35, v3
	v_rcp_f32_e32 v2, v32
	v_rcp_f32_e32 v3, v33
	s_waitcnt vmcnt(6)
	v_mul_f32_e32 v11, v41, v71
	v_lshlrev_b32_e32 v41, 2, v1
	v_mul_f32_e32 v6, v36, v66
	v_mul_f32_e32 v7, v37, v67
	v_mul_f32_e32 v8, v38, v68
	v_mul_f32_e32 v9, v39, v69
	v_mul_f32_e32 v10, v40, v70
	s_waitcnt vmcnt(5)
	v_mul_f32_e32 v12, v42, v72
	v_mul_f32_e32 v13, v43, v73
	v_mul_f32_e32 v14, v44, v74
	v_mul_f32_e32 v15, v45, v75
	s_waitcnt vmcnt(4)
	v_mul_f32_e32 v16, v46, v76
	v_mul_f32_e32 v17, v47, v77
	v_mul_f32_e32 v18, v48, v78
	v_mul_f32_e32 v19, v49, v79
	s_waitcnt vmcnt(3)
	v_mul_f32_e32 v20, v50, v80
	v_mul_f32_e32 v21, v51, v81
	v_mul_f32_e32 v22, v52, v82
	v_mul_f32_e32 v23, v53, v83
	s_waitcnt vmcnt(2)
	v_mul_f32_e32 v24, v54, v84
	v_mul_f32_e32 v25, v55, v85
	v_mul_f32_e32 v26, v56, v86
	v_mul_f32_e32 v27, v57, v87
	s_waitcnt vmcnt(1)
	v_mul_f32_e32 v28, v58, v88
	v_mul_f32_e32 v29, v59, v89
	v_mul_f32_e32 v30, v60, v90
	v_mul_f32_e32 v31, v61, v91
	s_waitcnt vmcnt(0)
	v_mul_f32_e32 v32, v62, v92
	v_mul_f32_e32 v33, v63, v93
	v_mul_f32_e32 v34, v64, v2
	v_mul_f32_e32 v35, v65, v3
	v_lshl_add_u64 v[2:3], s[0:1], 0, v[160:161]
	v_xor_b32_e32 v36, 0x80, v41
	v_xor_b32_e32 v37, 64, v41
	v_xor_b32_e32 v38, 32, v41
	v_xor_b32_e32 v39, 16, v41
	v_xor_b32_e32 v40, 8, v41
	v_xor_b32_e32 v41, 4, v41
	s_branch .LBB0_263
.LBB0_262:
	s_or_b64 exec, exec, s[0:1]
	v_readlane_b32 s0, v252, 45
	s_nop 1
	v_add_u32_e32 v0, 0x400, v0
	s_movk_i32 s0, 0x1fff
	v_cmp_lt_i32_e64 s[0:1], s0, v0
	s_or_b64 s[40:41], s[0:1], s[40:41]
	s_andn2_b64 exec, exec, s[40:41]
	s_cbranch_execz .LBB0_265

.Lmy_cvt0:
	v_readlane_b32 s0, v252, 47
	v_readlane_b32 s1, v252, 48
	s_andn2_b64 vcc, exec, s[0:1]
	s_cbranch_vccnz .LBB0_368
	s_cmp_lt_u32 s2, 0x80
	s_cbranch_scc1 .LBB0_368
	s_bfe_i64 s[0:1], s[52:53], 0x200000
	v_readlane_b32 s72, v252, 61
	s_lshl_b64 s[0:1], s[0:1], 13
	v_readlane_b32 s82, v253, 7
	v_readlane_b32 s83, v253, 8
	s_add_u32 s0, s82, s0
	s_addc_u32 s1, s83, s1
	s_mov_b64 s[6:7], s[38:39]
	v_readlane_b32 s36, v254, 50
	s_add_u32 s4, s0, 0xffffe000
	v_readlane_b32 s44, v254, 58
	v_readlane_b32 s80, v253, 5
	s_addc_u32 s5, s1, -1
	s_lshl_b64 s[0:1], s[52:53], 26
	s_lshl_b64 s[12:13], s[52:53], 13
	s_lshl_b64 s[18:19], s[52:53], 24
	s_lshl_b32 s16, s52, 4
	s_lshl_b64 s[20:21], s[52:53], 22
	v_readlane_b32 s38, v254, 52
	v_readlane_b32 s39, v254, 53
	s_lshl_b32 s44, s52, 9
	v_readlane_b32 s81, v253, 6
	s_mov_b64 s[38:39], s[6:7]
	s_add_u32 s6, s80, s0
	v_readlane_b32 s78, v253, 3
	s_addc_u32 s7, s81, s1
	v_readlane_b32 s79, v253, 4
	s_add_u32 s8, s78, s0
	v_readlane_b32 s74, v252, 63
	v_readlane_b32 s40, v254, 54
	s_addc_u32 s9, s79, s1
	v_readlane_b32 s75, v253, 0
	v_readlane_b32 s37, v254, 51
	v_readlane_b32 s41, v254, 55
	s_add_u32 s40, s74, s12
	v_readlane_b32 s42, v254, 56
	s_addc_u32 s41, s75, s13
	s_mov_b32 s1, s37
	v_readlane_b32 s73, v252, 62
	v_readlane_b32 s76, v253, 1
	v_readlane_b32 s77, v253, 2
	v_readlane_b32 s43, v254, 57
	v_readlane_b32 s45, v254, 59
	v_readlane_b32 s46, v254, 60
	v_readlane_b32 s47, v254, 61
	v_readlane_b32 s48, v254, 62
	v_readlane_b32 s49, v254, 63
	s_add_u32 s42, s72, s18
	v_writelane_b32 v254, s0, 50
	s_addc_u32 s43, s73, s19
	v_readlane_b32 s68, v252, 6
	v_writelane_b32 v254, s1, 51
	v_readlane_b32 s84, v253, 9
	v_readlane_b32 s85, v253, 10
	v_readlane_b32 s86, v253, 11
	v_readlane_b32 s87, v253, 12
	v_readlane_b32 s72, v252, 10
	v_readlane_b32 s73, v252, 11
	v_readlane_b32 s74, v252, 12
	v_readlane_b32 s75, v252, 13
	v_readlane_b32 s76, v252, 14
	v_readlane_b32 s77, v252, 15
	v_readlane_b32 s78, v252, 16
	v_readlane_b32 s79, v252, 17
	v_readlane_b32 s80, v252, 18
	v_readlane_b32 s81, v252, 19
	v_readlane_b32 s82, v252, 20
	v_readlane_b32 s83, v252, 21
	v_writelane_b32 v254, s2, 52
	v_writelane_b32 v254, s3, 53
	v_readlane_b32 s72, v252, 22
	v_writelane_b32 v254, s4, 54
	v_readlane_b32 s73, v252, 23
	v_readlane_b32 s74, v252, 24
	v_readlane_b32 s75, v252, 25
	v_readlane_b32 s76, v252, 26
	v_readlane_b32 s77, v252, 27
	v_readlane_b32 s78, v252, 28
	v_readlane_b32 s79, v252, 29
	v_readlane_b32 s80, v252, 30
	v_readlane_b32 s81, v252, 31
	v_readlane_b32 s82, v252, 32
	v_readlane_b32 s83, v252, 33
	v_readlane_b32 s50, v255, 0
	v_readlane_b32 s51, v255, 1
	s_mov_b32 s45, s37
	v_readlane_b32 s69, v252, 7
	s_add_u32 s46, s68, s20
	v_writelane_b32 v254, s5, 55
	v_writelane_b32 v255, s14, 0
	v_readlane_b32 s84, v252, 34
	v_readlane_b32 s85, v252, 35
	v_readlane_b32 s86, v252, 36
	v_readlane_b32 s87, v252, 37
	s_mov_b64 s[72:73], s[76:77]
	s_addc_u32 s47, s69, s21
	v_writelane_b32 v254, s6, 56
	v_writelane_b32 v255, s15, 1
	s_lshl_b64 s[0:1], s[44:45], 2
	s_mov_b64 s[74:75], s[78:79]
	s_mov_b64 s[76:77], s[80:81]
	s_mov_b64 s[78:79], s[82:83]
	s_mov_b64 s[80:81], s[84:85]
	v_writelane_b32 v254, s7, 57
	s_add_u32 s48, s80, s0
	s_mul_i32 s22, s52, 0x300000
	v_writelane_b32 v254, s8, 58
	s_mov_b64 s[82:83], s[86:87]
	s_addc_u32 s49, s81, s1
	s_mul_hi_u32 s17, s52, 0x300000
	v_writelane_b32 v254, s9, 59
	s_add_u32 s50, s82, s22
	v_writelane_b32 v254, s10, 60
	s_addc_u32 s51, s83, s17
	v_writelane_b32 v254, s11, 61
	s_add_u32 s58, s78, s0
	v_readlane_b32 s70, v252, 8
	v_writelane_b32 v254, s12, 62
	s_addc_u32 s59, s79, s1
	s_mul_i32 s1, s52, 0x1880000
	v_readlane_b32 s71, v252, 9
	v_writelane_b32 v254, s13, 63
	s_mul_hi_u32 s0, s52, 0x1880000
	s_add_u32 s70, s76, s1
	s_addc_u32 s71, s77, s0
	s_movk_i32 s17, 0x4000
	s_movk_i32 s18, 0x100
	v_readlane_b32 s19, v254, 38
	v_readlane_b32 s20, v254, 36
	v_readlane_b32 s21, v254, 32
	v_readlane_b32 s22, v252, 46
	s_nop 3
	s_addk_i32 s19, 0xf3e0
	s_addk_i32 s20, 0xcf80
	s_add_i32 s21, s21, 0xfffcf800
	s_addk_i32 s22, 0xf9f0
	s_branch .LBB0_269

.LBB0_651:
	v_readlane_b32 s0, v252, 45
	s_add_i32 s16, s16, s30
	s_add_i32 s15, s15, s13
	s_add_i32 s14, s14, s0
	s_cmpk_lt_i32 s16, 0x1a0
	s_cbranch_scc0 .LBB0_725
